# gdn_chunk_prep: gate inputs of the single-wave section before the barrier prefetched after the conv batch
# baseline (speedup 1.0000x reference)
.LBB0_363:
	v_mov_b32_e32 v68, v218
	s_load_dwordx2 s[80:81], s[36:37], 0x98
	s_load_dwordx2 s[92:93], s[36:37], 0x30
	s_ashr_i32 s2, s90, 10
	s_bfe_u32 s26, s90, 0x20008
	s_and_b32 s27, s90, 0xff
	v_ashrrev_i32_e32 v4, 2, v68
	s_waitcnt lgkmcnt(0)
	s_add_u32 s86, s80, 0x4000000
	s_addc_u32 s87, s81, 0
	s_ashr_i32 s3, s2, 31
	s_lshl_b64 s[40:41], s[2:3], 14
	s_lshl_b32 s2, s27, 6
	v_and_b32_e32 v5, -16, v4
	v_add_u32_e32 v7, s2, v5
	v_cmp_lt_i32_e64 s[44:45], 1, v7
	v_add_u32_e32 v8, -2, v5
	v_and_b32_e32 v34, 63, v68
	v_add_u32_e32 v0, -3, v5
	v_cmp_lt_i32_e64 s[42:43], 2, v7
	v_cndmask_b32_e64 v8, 0, v8, s[44:45]
	s_or_b32 s40, s40, s2
	v_cndmask_b32_e64 v0, 0, v0, s[42:43]
	v_lshl_or_b32 v6, s26, 6, v34
	v_ashrrev_i32_e32 v9, 31, v8
	v_ashrrev_i32_e32 v1, 31, v0
	v_lshlrev_b32_e32 v128, 1, v6
	v_lshl_add_u64 v[10:11], s[40:41], 0, v[8:9]
	v_mov_b64_e32 v[78:79], s[86:87]
	v_lshl_add_u64 v[2:3], s[40:41], 0, v[0:1]
	v_lshl_add_u64 v[0:1], s[86:87], 0, v[128:129]
	v_mad_u64_u32 v[84:85], s[2:3], v10, s10, v[78:79]
	v_mad_u64_u32 v[8:9], s[2:3], v10, s10, v[0:1]
	v_or_b32_e32 v82, 0x200, v128
	v_mov_b32_e32 v83, v129
	v_mad_i32_i24 v85, v11, s10, v85
	v_mad_i32_i24 v9, v11, s10, v9
	v_lshl_add_u64 v[10:11], v[84:85], 0, v[82:83]
	global_load_ushort v8, v[8:9], off
	v_cmp_lt_i32_e64 s[46:47], 0, v7
	global_load_ushort v30, v[10:11], off
	v_add_u32_e32 v9, -1, v5
	v_cndmask_b32_e64 v12, 0, v9, s[46:47]
	v_ashrrev_i32_e32 v13, 31, v12
	v_lshl_add_u64 v[12:13], s[40:41], 0, v[12:13]
	v_mad_u64_u32 v[86:87], s[2:3], v12, s10, v[78:79]
	v_mad_u64_u32 v[14:15], s[2:3], v12, s10, v[0:1]
	v_mad_i32_i24 v87, v13, s10, v87
	v_mad_i32_i24 v15, v13, s10, v15
	v_cmp_lt_i32_e64 s[48:49], -1, v7
	v_lshl_add_u64 v[10:11], v[86:87], 0, v[82:83]
	global_load_ushort v9, v[14:15], off
	global_load_ushort v31, v[10:11], off
	v_cndmask_b32_e64 v14, 0, v5, s[48:49]
	v_ashrrev_i32_e32 v15, 31, v14
	v_lshl_add_u64 v[14:15], s[40:41], 0, v[14:15]
	v_mad_u64_u32 v[88:89], s[2:3], v14, s10, v[78:79]
	v_mad_u64_u32 v[16:17], s[2:3], v14, s10, v[0:1]
	v_mad_i32_i24 v89, v15, s10, v89
	v_mad_i32_i24 v17, v15, s10, v17
	v_lshl_add_u64 v[10:11], v[88:89], 0, v[82:83]
	global_load_ushort v49, v[16:17], off
	global_load_ushort v32, v[10:11], off
	v_cmp_lt_i32_e64 s[50:51], -2, v7
	v_or_b32_e32 v16, 1, v5
	v_or_b32_e32 v128, 0x400, v128
	v_cndmask_b32_e64 v16, 0, v16, s[50:51]
	v_ashrrev_i32_e32 v17, 31, v16
	v_lshl_add_u64 v[16:17], s[40:41], 0, v[16:17]
	v_mad_u64_u32 v[14:15], s[2:3], v16, s10, v[78:79]
	v_mad_u64_u32 v[18:19], s[2:3], v16, s10, v[0:1]
	v_mad_i32_i24 v15, v17, s10, v15
	v_mad_i32_i24 v19, v17, s10, v19
	v_lshl_add_u64 v[10:11], v[14:15], 0, v[82:83]
	v_lshl_add_u64 v[14:15], v[14:15], 0, v[128:129]
	global_load_ushort v50, v[18:19], off
	global_load_ushort v33, v[10:11], off
	v_cmp_lt_i32_e64 s[52:53], -3, v7
	global_load_ushort v14, v[14:15], off
	v_or_b32_e32 v18, 2, v5
	v_cndmask_b32_e64 v18, 0, v18, s[52:53]
	v_ashrrev_i32_e32 v19, 31, v18
	v_lshl_add_u64 v[18:19], s[40:41], 0, v[18:19]
	v_mad_u64_u32 v[16:17], s[2:3], v18, s10, v[78:79]
	v_mad_u64_u32 v[20:21], s[2:3], v18, s10, v[0:1]
	v_mad_i32_i24 v17, v19, s10, v17
	v_mad_i32_i24 v21, v19, s10, v21
	v_lshl_add_u64 v[10:11], v[16:17], 0, v[82:83]
	v_lshl_add_u64 v[16:17], v[16:17], 0, v[128:129]
	global_load_ushort v51, v[20:21], off
	global_load_ushort v35, v[10:11], off
	global_load_ushort v15, v[16:17], off
	v_cmp_lt_i32_e64 s[54:55], -4, v7
	v_or_b32_e32 v20, 3, v5
	v_cmp_lt_i32_e64 s[56:57], -5, v7
	v_cndmask_b32_e64 v20, 0, v20, s[54:55]
	v_ashrrev_i32_e32 v21, 31, v20
	v_lshl_add_u64 v[20:21], s[40:41], 0, v[20:21]
	v_mad_u64_u32 v[18:19], s[2:3], v20, s10, v[78:79]
	v_mad_u64_u32 v[22:23], s[2:3], v20, s10, v[0:1]
	v_mad_i32_i24 v19, v21, s10, v19
	v_mad_i32_i24 v23, v21, s10, v23
	v_lshl_add_u64 v[10:11], v[18:19], 0, v[82:83]
	v_lshl_add_u64 v[16:17], v[18:19], 0, v[128:129]
	global_load_ushort v52, v[22:23], off
	global_load_ushort v36, v[10:11], off
	v_cmp_lt_i32_e64 s[58:59], -6, v7
	global_load_ushort v16, v[16:17], off
	v_or_b32_e32 v22, 4, v5
	v_cndmask_b32_e64 v22, 0, v22, s[56:57]
	v_ashrrev_i32_e32 v23, 31, v22
	v_lshl_add_u64 v[22:23], s[40:41], 0, v[22:23]
	v_mad_u64_u32 v[20:21], s[2:3], v22, s10, v[78:79]
	v_mad_u64_u32 v[24:25], s[2:3], v22, s10, v[0:1]
	v_mad_i32_i24 v21, v23, s10, v21
	v_mad_i32_i24 v25, v23, s10, v25
	v_lshl_add_u64 v[10:11], v[20:21], 0, v[82:83]
	v_lshl_add_u64 v[18:19], v[20:21], 0, v[128:129]
	global_load_ushort v53, v[24:25], off
	global_load_ushort v37, v[10:11], off
	global_load_ushort v17, v[18:19], off
	v_or_b32_e32 v24, 5, v5
	v_cndmask_b32_e64 v24, 0, v24, s[58:59]
	v_ashrrev_i32_e32 v25, 31, v24
	v_lshl_add_u64 v[24:25], s[40:41], 0, v[24:25]
	v_mad_u64_u32 v[22:23], s[2:3], v24, s10, v[78:79]
	v_mad_u64_u32 v[26:27], s[2:3], v24, s10, v[0:1]
	v_mad_i32_i24 v23, v25, s10, v23
	v_mad_i32_i24 v27, v25, s10, v27
	v_lshl_add_u64 v[10:11], v[22:23], 0, v[82:83]
	v_lshl_add_u64 v[18:19], v[22:23], 0, v[128:129]
	global_load_ushort v54, v[26:27], off
	global_load_ushort v38, v[10:11], off
	v_cmp_lt_i32_e64 s[60:61], -7, v7
	global_load_ushort v18, v[18:19], off
	v_or_b32_e32 v26, 6, v5
	v_cndmask_b32_e64 v26, 0, v26, s[60:61]
	v_ashrrev_i32_e32 v27, 31, v26
	v_lshl_add_u64 v[26:27], s[40:41], 0, v[26:27]
	v_mad_u64_u32 v[24:25], s[2:3], v26, s10, v[78:79]
	v_mad_u64_u32 v[28:29], s[2:3], v26, s10, v[0:1]
	v_mad_i32_i24 v25, v27, s10, v25
	v_mad_i32_i24 v29, v27, s10, v29
	v_lshl_add_u64 v[10:11], v[24:25], 0, v[82:83]
	v_lshl_add_u64 v[20:21], v[24:25], 0, v[128:129]
	global_load_ushort v55, v[28:29], off
	global_load_ushort v39, v[10:11], off
	global_load_ushort v19, v[20:21], off
	v_cmp_lt_i32_e64 s[62:63], -8, v7
	v_or_b32_e32 v28, 7, v5
	v_cmp_lt_i32_e64 s[64:65], -9, v7
	v_cndmask_b32_e64 v28, 0, v28, s[62:63]
	v_ashrrev_i32_e32 v29, 31, v28
	v_lshl_add_u64 v[40:41], s[40:41], 0, v[28:29]
	v_mad_u64_u32 v[26:27], s[2:3], v40, s10, v[78:79]
	v_mad_u64_u32 v[28:29], s[2:3], v40, s10, v[0:1]
	v_mad_i32_i24 v27, v41, s10, v27
	v_mad_i32_i24 v29, v41, s10, v29
	v_lshl_add_u64 v[10:11], v[26:27], 0, v[82:83]
	v_lshl_add_u64 v[20:21], v[26:27], 0, v[128:129]
	global_load_ushort v56, v[28:29], off
	global_load_ushort v40, v[10:11], off
	v_cmp_lt_i32_e64 s[66:67], -10, v7
	global_load_ushort v20, v[20:21], off
	v_or_b32_e32 v28, 8, v5
	v_cndmask_b32_e64 v28, 0, v28, s[64:65]
	v_ashrrev_i32_e32 v29, 31, v28
	v_lshl_add_u64 v[42:43], s[40:41], 0, v[28:29]
	v_mad_u64_u32 v[90:91], s[2:3], v42, s10, v[78:79]
	v_mad_u64_u32 v[28:29], s[2:3], v42, s10, v[0:1]
	v_mad_i32_i24 v91, v43, s10, v91
	v_mad_i32_i24 v29, v43, s10, v29
	v_lshl_add_u64 v[10:11], v[90:91], 0, v[82:83]
	v_lshl_add_u64 v[22:23], v[90:91], 0, v[128:129]
	global_load_ushort v57, v[28:29], off
	global_load_ushort v41, v[10:11], off
	global_load_ushort v21, v[22:23], off
	v_or_b32_e32 v28, 9, v5
	v_cndmask_b32_e64 v28, 0, v28, s[66:67]
	v_ashrrev_i32_e32 v29, 31, v28
	v_lshl_add_u64 v[44:45], s[40:41], 0, v[28:29]
	v_mad_u64_u32 v[92:93], s[2:3], v44, s10, v[78:79]
	v_mad_u64_u32 v[28:29], s[2:3], v44, s10, v[0:1]
	v_mad_i32_i24 v93, v45, s10, v93
	v_mad_i32_i24 v29, v45, s10, v29
	v_lshl_add_u64 v[10:11], v[92:93], 0, v[82:83]
	v_lshl_add_u64 v[22:23], v[92:93], 0, v[128:129]
	global_load_ushort v58, v[28:29], off
	global_load_ushort v42, v[10:11], off
	v_cmp_lt_i32_e64 s[68:69], -11, v7
	global_load_ushort v22, v[22:23], off
	v_or_b32_e32 v28, 10, v5
	v_cndmask_b32_e64 v28, 0, v28, s[68:69]
	v_ashrrev_i32_e32 v29, 31, v28
	v_lshl_add_u64 v[46:47], s[40:41], 0, v[28:29]
	v_mad_u64_u32 v[94:95], s[2:3], v46, s10, v[78:79]
	v_mad_u64_u32 v[28:29], s[2:3], v46, s10, v[0:1]
	v_mad_i32_i24 v95, v47, s10, v95
	v_mad_i32_i24 v29, v47, s10, v29
	v_lshl_add_u64 v[10:11], v[94:95], 0, v[82:83]
	v_lshl_add_u64 v[24:25], v[94:95], 0, v[128:129]
	global_load_ushort v59, v[28:29], off
	global_load_ushort v43, v[10:11], off
	global_load_ushort v23, v[24:25], off
	v_cmp_lt_i32_e64 s[70:71], -12, v7
	v_or_b32_e32 v28, 11, v5
	v_cmp_lt_i32_e64 s[72:73], -13, v7
	v_cndmask_b32_e64 v28, 0, v28, s[70:71]
	v_ashrrev_i32_e32 v29, 31, v28
	v_lshl_add_u64 v[66:67], s[40:41], 0, v[28:29]
	v_mad_u64_u32 v[96:97], s[2:3], v66, s10, v[78:79]
	v_mad_u64_u32 v[28:29], s[2:3], v66, s10, v[0:1]
	v_mad_i32_i24 v97, v67, s10, v97
	v_mad_i32_i24 v29, v67, s10, v29
	v_lshl_add_u64 v[10:11], v[96:97], 0, v[82:83]
	v_lshl_add_u64 v[24:25], v[96:97], 0, v[128:129]
	global_load_ushort v60, v[28:29], off
	global_load_ushort v44, v[10:11], off
	v_cmp_lt_i32_e64 s[74:75], -14, v7
	global_load_ushort v24, v[24:25], off
	v_or_b32_e32 v28, 12, v5
	v_cndmask_b32_e64 v28, 0, v28, s[72:73]
	v_ashrrev_i32_e32 v29, 31, v28
	v_lshl_add_u64 v[70:71], s[40:41], 0, v[28:29]
	v_mad_u64_u32 v[66:67], s[2:3], v70, s10, v[78:79]
	v_mad_u64_u32 v[28:29], s[2:3], v70, s10, v[0:1]
	v_mad_i32_i24 v67, v71, s10, v67
	v_mad_i32_i24 v29, v71, s10, v29
	v_lshl_add_u64 v[10:11], v[66:67], 0, v[82:83]
	v_lshl_add_u64 v[26:27], v[66:67], 0, v[128:129]
	global_load_ushort v61, v[28:29], off
	global_load_ushort v45, v[10:11], off
	global_load_ushort v25, v[26:27], off
	v_or_b32_e32 v28, 13, v5
	v_cndmask_b32_e64 v28, 0, v28, s[74:75]
	v_ashrrev_i32_e32 v29, 31, v28
	v_lshl_add_u64 v[72:73], s[40:41], 0, v[28:29]
	v_mad_u64_u32 v[70:71], s[2:3], v72, s10, v[78:79]
	v_mad_u64_u32 v[28:29], s[2:3], v72, s10, v[0:1]
	v_mad_i32_i24 v71, v73, s10, v71
	v_mad_i32_i24 v29, v73, s10, v29
	v_lshl_add_u64 v[10:11], v[70:71], 0, v[82:83]
	v_lshl_add_u64 v[26:27], v[70:71], 0, v[128:129]
	global_load_ushort v62, v[28:29], off
	global_load_ushort v46, v[10:11], off
	v_cmp_lt_i32_e64 s[76:77], -15, v7
	global_load_ushort v26, v[26:27], off
	v_or_b32_e32 v28, 14, v5
	v_cndmask_b32_e64 v28, 0, v28, s[76:77]
	v_ashrrev_i32_e32 v29, 31, v28
	v_lshl_add_u64 v[74:75], s[40:41], 0, v[28:29]
	v_mad_u64_u32 v[72:73], s[2:3], v74, s10, v[78:79]
	v_mad_u64_u32 v[28:29], s[2:3], v74, s10, v[0:1]
	v_mad_i32_i24 v73, v75, s10, v73
	v_mad_i32_i24 v29, v75, s10, v29
	v_cmp_lt_i32_e64 s[78:79], -16, v7
	v_or_b32_e32 v4, 15, v4
	v_lshl_add_u64 v[10:11], v[72:73], 0, v[82:83]
	global_load_ushort v63, v[28:29], off
	global_load_ushort v47, v[10:11], off
	v_cndmask_b32_e64 v28, 0, v4, s[78:79]
	v_ashrrev_i32_e32 v29, 31, v28
	s_load_dwordx2 s[86:87], s[36:37], 0x20
	v_lshl_add_u64 v[76:77], s[40:41], 0, v[28:29]
	v_mad_u64_u32 v[28:29], s[2:3], v76, s10, v[0:1]
	v_mad_u64_u32 v[80:81], s[2:3], v2, s10, v[78:79]
	v_mad_u64_u32 v[74:75], s[2:3], v76, s10, v[78:79]
	v_mad_i32_i24 v75, v77, s10, v75
	v_readlane_b32 s2, v255, 30
	v_mad_i32_i24 v29, v77, s10, v29
	v_mad_i32_i24 v81, v3, s10, v81
	v_lshl_add_u64 v[10:11], v[74:75], 0, v[82:83]
	s_mul_i32 s28, s2, 0x3000
	global_load_ushort v64, v[28:29], off
	global_load_ushort v48, v[10:11], off
	v_lshl_add_u64 v[28:29], v[80:81], 0, v[82:83]
	v_lshl_add_u64 v[10:11], v[80:81], 0, v[128:129]
	v_lshl_add_u64 v[12:13], v[84:85], 0, v[128:129]
	v_lshl_add_u64 v[66:67], v[72:73], 0, v[128:129]
	v_readlane_b32 s3, v255, 31
	s_waitcnt lgkmcnt(0)
	s_add_u32 s2, s86, s28
	global_load_ushort v29, v[28:29], off
	v_lshl_add_u64 v[76:77], v[88:89], 0, v[128:129]
	global_load_ushort v10, v[10:11], off
	s_addc_u32 s3, s87, 0
	global_load_ushort v11, v[12:13], off
	global_load_ushort v27, v[66:67], off
	v_lshl_add_u64 v[12:13], v[86:87], 0, v[128:129]
	v_lshl_add_u64 v[66:67], v[74:75], 0, v[128:129]
	v_lshlrev_b32_e32 v128, 2, v6
	v_lshl_add_u64 v[6:7], s[2:3], 0, v[128:129]
	v_add_co_u32_e32 v70, vcc, 0x1000, v6
	global_load_ushort v12, v[12:13], off
	s_nop 0
	v_addc_co_u32_e32 v71, vcc, 0, v7, vcc
	global_load_ushort v28, v[66:67], off
	global_load_ushort v13, v[76:77], off
	global_load_dword v65, v128, s[2:3]
	s_nop 0
	global_load_dword v66, v128, s[2:3] offset:3072
	global_load_dword v67, v[70:71], off offset:2048
	v_add_co_u32_e32 v70, vcc, 0x2000, v6
	s_nop 1
	v_addc_co_u32_e32 v71, vcc, 0, v7, vcc
	global_load_dword v69, v[70:71], off offset:1024
	v_mov_b32_e32 v70, 0
	s_and_saveexec_b64 s[86:87], s[42:43]
	s_cbranch_execz .LBB0_365
	v_mad_u64_u32 v[70:71], s[2:3], v2, s10, 0
	v_mad_i32_i24 v71, v3, s10, v71
	v_lshl_add_u64 v[0:1], v[0:1], 0, v[70:71]
	global_load_ushort v0, v[0:1], off
	s_waitcnt vmcnt(0)
	v_lshlrev_b32_e32 v70, 16, v0
.LBB0_365:
	s_or_b64 exec, exec, s[86:87]
	s_waitcnt vmcnt(59)
	v_lshlrev_b32_e32 v0, 16, v8
	v_cndmask_b32_e64 v1, 0, v0, s[44:45]
	s_waitcnt vmcnt(57)
	v_lshlrev_b32_e32 v0, 16, v9
	v_cndmask_b32_e64 v8, 0, v0, s[46:47]
	s_waitcnt vmcnt(55)
	v_lshlrev_b32_e32 v0, 16, v49
	v_cndmask_b32_e64 v9, 0, v0, s[48:49]
	s_waitcnt vmcnt(53)
	v_lshlrev_b32_e32 v0, 16, v50
	v_cndmask_b32_e64 v49, 0, v0, s[50:51]
	s_waitcnt vmcnt(50)
	v_lshlrev_b32_e32 v0, 16, v51
	v_cndmask_b32_e64 v50, 0, v0, s[52:53]
	s_waitcnt vmcnt(47)
	v_lshlrev_b32_e32 v0, 16, v52
	s_waitcnt vmcnt(3)
	v_mul_f32_e32 v2, v65, v70
	v_cndmask_b32_e64 v51, 0, v0, s[54:55]
	v_lshlrev_b32_e32 v0, 16, v53
	s_waitcnt vmcnt(2)
	v_fmac_f32_e32 v2, v1, v66
	v_cndmask_b32_e64 v52, 0, v0, s[56:57]
	v_lshlrev_b32_e32 v0, 16, v54
	s_waitcnt vmcnt(1)
	v_fmac_f32_e32 v2, v8, v67
	v_cndmask_b32_e64 v53, 0, v0, s[58:59]
	v_lshlrev_b32_e32 v0, 16, v55
	s_waitcnt vmcnt(0)
	s_load_dwordx2 s[2:3], s[36:37], 0x28
	v_mov_b32_e32 v216, v68
	v_mov_b32_e32 v217, 0
	v_lshl_add_u64 v[216:217], s[40:41], 0, v[216:217]
	v_lshlrev_b64 v[216:217], 7, v[216:217]
	v_lshl_add_u64 v[216:217], s[80:81], 0, v[216:217]
	s_lshl_b32 vcc_lo, s26, 2
	s_mov_b32 vcc_hi, 0
	v_lshl_add_u64 v[216:217], v[216:217], 0, vcc
	s_mov_b64 vcc, 0x10000000
	v_lshl_add_u64 v[216:217], v[216:217], 0, vcc
	global_load_dword v200, v[216:217], off offset:16
	global_load_dword v201, v[216:217], off
	s_or_b32 vcc_lo, s26, s94
	s_lshl_b32 vcc_lo, vcc_lo, 2
	s_add_u32 s92, s92, vcc_lo
	s_addc_u32 s93, s93, 0
	global_load_dword v202, v129, s[92:93]
	s_waitcnt lgkmcnt(0)
	s_add_u32 s2, s2, vcc_lo
	s_addc_u32 s3, s3, 0
	global_load_dword v203, v129, s[2:3]
	s_mov_b64 s[2:3], 0x1000
	v_lshl_add_u64 v[212:213], v[6:7], 0, s[2:3]
	s_mov_b64 s[2:3], 0x2000
	v_lshl_add_u64 v[214:215], v[6:7], 0, s[2:3]
	global_load_dword v204, v[6:7], off offset:1024
	global_load_dword v205, v[212:213], off
	global_load_dword v206, v[212:213], off offset:3072
	global_load_dword v207, v[214:215], off offset:2048
	global_load_dword v208, v[6:7], off offset:2048
	global_load_dword v209, v[212:213], off offset:1024
	global_load_dword v210, v[214:215], off
	global_load_dword v211, v[214:215], off offset:3072
	v_fmac_f32_e32 v2, v9, v69
	v_cndmask_b32_e64 v54, 0, v0, s[60:61]
	v_lshlrev_b32_e32 v0, 16, v56
	v_mul_f32_e32 v3, 0xbfb8aa3b, v2
	v_cndmask_b32_e64 v55, 0, v0, s[62:63]
	v_lshlrev_b32_e32 v0, 16, v57
	v_exp_f32_e32 v3, v3
	v_cndmask_b32_e64 v56, 0, v0, s[64:65]
	v_lshlrev_b32_e32 v0, 16, v58
	v_cndmask_b32_e64 v57, 0, v0, s[66:67]
	v_lshlrev_b32_e32 v0, 16, v59
	v_cndmask_b32_e64 v58, 0, v0, s[68:69]
	v_lshlrev_b32_e32 v0, 16, v60
	v_cndmask_b32_e64 v59, 0, v0, s[70:71]
	v_lshlrev_b32_e32 v0, 16, v61
	v_add_f32_e32 v3, 1.0, v3
	v_cndmask_b32_e64 v60, 0, v0, s[72:73]
	v_lshlrev_b32_e32 v0, 16, v62
	v_rcp_f32_e32 v3, v3
	v_cndmask_b32_e64 v61, 0, v0, s[74:75]
	v_lshlrev_b32_e32 v0, 16, v63
	s_and_b32 s2, s90, 0xfffffc00
	s_lshl_b32 s3, s26, 8
	v_cndmask_b32_e64 v62, 0, v0, s[76:77]
	v_lshlrev_b32_e32 v0, 16, v64
	s_or_b32 s2, s3, s2
	v_cndmask_b32_e64 v63, 0, v0, s[78:79]
	v_lshlrev_b32_e32 v0, 2, v34
	s_or_b32 s86, s2, s27
	v_mul_f32_e32 v64, v2, v3
	v_mad_u64_u32 v[2:3], s[2:3], v5, s33, v[0:1]
	v_mul_f32_e32 v3, v8, v66
	v_fmac_f32_e32 v3, v1, v65
	v_fmac_f32_e32 v3, v9, v67
	v_fmac_f32_e32 v3, v49, v69
	v_mul_f32_e32 v1, 0xbfb8aa3b, v3
	v_exp_f32_e32 v1, v1
	v_lshlrev_b32_e32 v30, 16, v30
	v_lshlrev_b32_e32 v29, 16, v29
	v_cndmask_b32_e64 v30, 0, v30, s[44:45]
	v_add_f32_e32 v1, 1.0, v1
	v_rcp_f32_e32 v1, v1
	v_cndmask_b32_e64 v29, 0, v29, s[42:43]
	v_lshlrev_b32_e32 v31, 16, v31
	v_cndmask_b32_e64 v31, 0, v31, s[46:47]
	v_mul_f32_e32 v1, v3, v1
	ds_write2_b32 v2, v64, v1 offset1:65
	v_mul_f32_e32 v1, v9, v66
	v_fmac_f32_e32 v1, v8, v65
	v_fmac_f32_e32 v1, v49, v67
	v_fmac_f32_e32 v1, v50, v69
	v_mul_f32_e32 v3, 0xbfb8aa3b, v1
	v_exp_f32_e32 v3, v3
	v_lshlrev_b32_e32 v32, 16, v32
	v_cndmask_b32_e64 v32, 0, v32, s[48:49]
	v_lshlrev_b32_e32 v33, 16, v33
	v_add_f32_e32 v3, 1.0, v3
	v_rcp_f32_e32 v3, v3
	v_cndmask_b32_e64 v33, 0, v33, s[50:51]
	v_lshlrev_b32_e32 v35, 16, v35
	v_cndmask_b32_e64 v35, 0, v35, s[52:53]
	v_mul_f32_e32 v1, v1, v3
	v_mul_f32_e32 v3, v49, v66
	v_fmac_f32_e32 v3, v9, v65
	v_fmac_f32_e32 v3, v50, v67
	v_fmac_f32_e32 v3, v51, v69
	v_mul_f32_e32 v5, 0xbfb8aa3b, v3
	v_exp_f32_e32 v5, v5
	v_lshlrev_b32_e32 v36, 16, v36
	v_cndmask_b32_e64 v36, 0, v36, s[54:55]
	v_lshlrev_b32_e32 v37, 16, v37
	v_add_f32_e32 v5, 1.0, v5
	v_rcp_f32_e32 v5, v5
	v_cndmask_b32_e64 v37, 0, v37, s[56:57]
	v_lshlrev_b32_e32 v38, 16, v38
	v_cndmask_b32_e64 v38, 0, v38, s[58:59]
	v_mul_f32_e32 v3, v3, v5
	ds_write2_b32 v2, v1, v3 offset0:130 offset1:195
	v_mul_f32_e32 v1, v50, v66
	v_fmac_f32_e32 v1, v49, v65
	v_fmac_f32_e32 v1, v51, v67
	v_fmac_f32_e32 v1, v52, v69
	v_mul_f32_e32 v3, 0xbfb8aa3b, v1
	v_exp_f32_e32 v3, v3
	v_lshlrev_b32_e32 v39, 16, v39
	v_cndmask_b32_e64 v39, 0, v39, s[60:61]
	v_lshlrev_b32_e32 v40, 16, v40
	v_add_f32_e32 v3, 1.0, v3
	v_rcp_f32_e32 v3, v3
	v_cndmask_b32_e64 v40, 0, v40, s[62:63]
	v_lshlrev_b32_e32 v41, 16, v41
	v_cndmask_b32_e64 v41, 0, v41, s[64:65]
	v_mul_f32_e32 v1, v1, v3
	v_mul_f32_e32 v3, v51, v66
	v_fmac_f32_e32 v3, v50, v65
	v_fmac_f32_e32 v3, v52, v67
	v_fmac_f32_e32 v3, v53, v69
	v_mul_f32_e32 v5, 0xbfb8aa3b, v3
	v_exp_f32_e32 v5, v5
	v_lshlrev_b32_e32 v42, 16, v42
	v_cndmask_b32_e64 v42, 0, v42, s[66:67]
	v_lshlrev_b32_e32 v43, 16, v43
	v_add_f32_e32 v5, 1.0, v5
	v_rcp_f32_e32 v5, v5
	v_cndmask_b32_e64 v43, 0, v43, s[68:69]
	v_lshlrev_b32_e32 v44, 16, v44
	v_cndmask_b32_e64 v44, 0, v44, s[70:71]
	v_mul_f32_e32 v3, v3, v5
	v_add_u32_e32 v5, 0x400, v2
	ds_write2_b32 v5, v1, v3 offset0:4 offset1:69
	v_mul_f32_e32 v1, v52, v66
	v_fmac_f32_e32 v1, v51, v65
	v_fmac_f32_e32 v1, v53, v67
	v_fmac_f32_e32 v1, v54, v69
	v_mul_f32_e32 v3, 0xbfb8aa3b, v1
	v_exp_f32_e32 v3, v3
	v_lshlrev_b32_e32 v45, 16, v45
	v_cndmask_b32_e64 v45, 0, v45, s[72:73]
	v_lshlrev_b32_e32 v46, 16, v46
	v_add_f32_e32 v3, 1.0, v3
	v_rcp_f32_e32 v3, v3
	v_cndmask_b32_e64 v46, 0, v46, s[74:75]
	v_lshlrev_b32_e32 v47, 16, v47
	v_cndmask_b32_e64 v47, 0, v47, s[76:77]
	v_mul_f32_e32 v1, v1, v3
	v_mul_f32_e32 v3, v53, v66
	v_fmac_f32_e32 v3, v52, v65
	v_fmac_f32_e32 v3, v54, v67
	v_fmac_f32_e32 v3, v55, v69
	v_mul_f32_e32 v8, 0xbfb8aa3b, v3
	v_exp_f32_e32 v8, v8
	v_lshlrev_b32_e32 v48, 16, v48
	v_cndmask_b32_e64 v48, 0, v48, s[78:79]
	s_ashr_i32 s87, s86, 31
	v_add_f32_e32 v8, 1.0, v8
	v_rcp_f32_e32 v8, v8
	s_nop 0
	v_mul_f32_e32 v3, v3, v8
	ds_write2_b32 v5, v1, v3 offset0:134 offset1:199
	v_mul_f32_e32 v1, v54, v66
	v_fmac_f32_e32 v1, v53, v65
	v_fmac_f32_e32 v1, v55, v67
	v_fmac_f32_e32 v1, v56, v69
	v_mul_f32_e32 v3, 0xbfb8aa3b, v1
	v_exp_f32_e32 v3, v3
	s_nop 0
	v_add_f32_e32 v3, 1.0, v3
	v_rcp_f32_e32 v3, v3
	s_nop 0
	v_mul_f32_e32 v1, v1, v3
	v_mul_f32_e32 v3, v55, v66
	v_fmac_f32_e32 v3, v54, v65
	v_fmac_f32_e32 v3, v56, v67
	v_fmac_f32_e32 v3, v57, v69
	v_mul_f32_e32 v5, 0xbfb8aa3b, v3
	v_exp_f32_e32 v5, v5
	s_nop 0
	v_add_f32_e32 v5, 1.0, v5
	v_rcp_f32_e32 v5, v5
	s_nop 0
	v_mul_f32_e32 v3, v3, v5
	v_add_u32_e32 v5, 0x800, v2
	ds_write2_b32 v5, v1, v3 offset0:8 offset1:73
	v_mul_f32_e32 v1, v56, v66
	v_fmac_f32_e32 v1, v55, v65
	v_fmac_f32_e32 v1, v57, v67
	v_fmac_f32_e32 v1, v58, v69
	v_mul_f32_e32 v3, 0xbfb8aa3b, v1
	v_exp_f32_e32 v3, v3
	s_nop 0
	v_add_f32_e32 v3, 1.0, v3
	v_rcp_f32_e32 v3, v3
	s_nop 0
	v_mul_f32_e32 v1, v1, v3
	v_mul_f32_e32 v3, v57, v66
	v_fmac_f32_e32 v3, v56, v65
	v_fmac_f32_e32 v3, v58, v67
	v_fmac_f32_e32 v3, v59, v69
	v_mul_f32_e32 v8, 0xbfb8aa3b, v3
	v_exp_f32_e32 v8, v8
	s_nop 0
	v_add_f32_e32 v8, 1.0, v8
	v_rcp_f32_e32 v8, v8
	s_nop 0
	v_mul_f32_e32 v3, v3, v8
	ds_write2_b32 v5, v1, v3 offset0:138 offset1:203
	v_mul_f32_e32 v1, v58, v66
	v_fmac_f32_e32 v1, v57, v65
	v_fmac_f32_e32 v1, v59, v67
	v_fmac_f32_e32 v1, v60, v69
	v_mul_f32_e32 v3, 0xbfb8aa3b, v1
	v_exp_f32_e32 v3, v3
	s_nop 0
	v_add_f32_e32 v3, 1.0, v3
	v_rcp_f32_e32 v3, v3
	s_nop 0
	v_mul_f32_e32 v1, v1, v3
	v_mul_f32_e32 v3, v59, v66
	v_fmac_f32_e32 v3, v58, v65
	v_fmac_f32_e32 v3, v60, v67
	v_fmac_f32_e32 v3, v61, v69
	v_mul_f32_e32 v5, 0xbfb8aa3b, v3
	v_exp_f32_e32 v5, v5
	s_nop 0
	v_add_f32_e32 v5, 1.0, v5
	v_rcp_f32_e32 v5, v5
	s_nop 0
	v_mul_f32_e32 v3, v3, v5
	v_add_u32_e32 v5, 0xc00, v2
	ds_write2_b32 v5, v1, v3 offset0:12 offset1:77
	v_mul_f32_e32 v1, v60, v66
	v_fmac_f32_e32 v1, v59, v65
	v_fmac_f32_e32 v1, v61, v67
	v_fmac_f32_e32 v1, v62, v69
	v_mul_f32_e32 v3, 0xbfb8aa3b, v1
	v_exp_f32_e32 v3, v3
	s_nop 0
	v_add_f32_e32 v3, 1.0, v3
	v_rcp_f32_e32 v3, v3
	s_nop 0
	v_mul_f32_e32 v1, v1, v3
	ds_write_b32 v2, v1 offset:3640
	v_mul_f32_e32 v1, v61, v66
	v_fmac_f32_e32 v1, v60, v65
	v_fmac_f32_e32 v1, v62, v67
	v_fmac_f32_e32 v1, v63, v69
	v_mul_f32_e32 v3, 0xbfb8aa3b, v1
	v_exp_f32_e32 v3, v3
	s_nop 0
	v_add_f32_e32 v3, 1.0, v3
	v_rcp_f32_e32 v3, v3
	s_nop 0
	v_mul_f32_e32 v1, v1, v3
	v_mad_u64_u32 v[4:5], s[2:3], v4, s33, v[0:1]
	s_mov_b64 s[2:3], 0x400
	ds_write_b32 v4, v1
	v_lshl_add_u64 v[8:9], v[6:7], 0, s[2:3]
	s_movk_i32 s2, 0x1000
	s_waitcnt vmcnt(0)
	v_add_co_u32_e32 v8, vcc, s2, v6
	s_movk_i32 s2, 0x2000
	s_nop 0
	v_addc_co_u32_e32 v9, vcc, 0, v7, vcc
	v_add_co_u32_e32 v8, vcc, s2, v6
	v_mul_f32_e32 v50, v30, v205
	v_addc_co_u32_e32 v9, vcc, 0, v7, vcc
	v_fmac_f32_e32 v50, v29, v204
	s_mov_b64 vcc, 0x800
	v_fmac_f32_e32 v50, v31, v206
	v_fmac_f32_e32 v50, v32, v207
	v_mul_f32_e32 v29, 0xbfb8aa3b, v50
	v_exp_f32_e32 v29, v29
	s_nop 0
	v_add_f32_e32 v29, 1.0, v29
	v_rcp_f32_e32 v29, v29
	s_nop 0
	v_mul_f32_e32 v29, v50, v29
	v_mul_f32_e32 v50, v31, v205
	v_fmac_f32_e32 v50, v30, v204
	v_fmac_f32_e32 v50, v32, v206
	v_fmac_f32_e32 v50, v33, v207
	v_mul_f32_e32 v30, 0xbfb8aa3b, v50
	v_exp_f32_e32 v30, v30
	s_nop 0
	v_add_f32_e32 v30, 1.0, v30
	v_rcp_f32_e32 v30, v30
	s_nop 0
	v_mul_f32_e32 v30, v50, v30
	v_add_u32_e32 v50, 0x4000, v2
	ds_write2_b32 v50, v29, v30 offset0:64 offset1:129
	v_mul_f32_e32 v29, v32, v205
	v_fmac_f32_e32 v29, v31, v204
	v_fmac_f32_e32 v29, v33, v206
	v_fmac_f32_e32 v29, v35, v207
	v_mul_f32_e32 v30, 0xbfb8aa3b, v29
	v_exp_f32_e32 v30, v30
	s_nop 0
	v_add_f32_e32 v30, 1.0, v30
	v_rcp_f32_e32 v30, v30
	s_nop 0
	v_mul_f32_e32 v29, v29, v30
	v_mul_f32_e32 v30, v33, v205
	v_fmac_f32_e32 v30, v32, v204
	v_fmac_f32_e32 v30, v35, v206
	v_fmac_f32_e32 v30, v36, v207
	v_mul_f32_e32 v31, 0xbfb8aa3b, v30
	v_exp_f32_e32 v31, v31
	s_nop 0
	v_add_f32_e32 v31, 1.0, v31
	v_rcp_f32_e32 v31, v31
	s_nop 0
	v_mul_f32_e32 v30, v30, v31
	v_add_u32_e32 v31, 0x4200, v2
	ds_write2_b32 v31, v29, v30 offset0:66 offset1:131
	v_mul_f32_e32 v29, v35, v205
	v_fmac_f32_e32 v29, v33, v204
	v_fmac_f32_e32 v29, v36, v206
	v_fmac_f32_e32 v29, v37, v207
	v_mul_f32_e32 v30, 0xbfb8aa3b, v29
	v_exp_f32_e32 v30, v30
	s_nop 0
	v_add_f32_e32 v30, 1.0, v30
	v_rcp_f32_e32 v30, v30
	s_nop 0
	v_mul_f32_e32 v29, v29, v30
	v_mul_f32_e32 v30, v36, v205
	v_fmac_f32_e32 v30, v35, v204
	v_fmac_f32_e32 v30, v37, v206
	v_fmac_f32_e32 v30, v38, v207
	v_mul_f32_e32 v31, 0xbfb8aa3b, v30
	v_exp_f32_e32 v31, v31
	s_nop 0
	v_add_f32_e32 v31, 1.0, v31
	v_rcp_f32_e32 v31, v31
	s_nop 0
	v_mul_f32_e32 v30, v30, v31
	v_add_u32_e32 v31, 0x4400, v2
	ds_write2_b32 v31, v29, v30 offset0:68 offset1:133
	v_mul_f32_e32 v29, v37, v205
	v_fmac_f32_e32 v29, v36, v204
	v_fmac_f32_e32 v29, v38, v206
	v_fmac_f32_e32 v29, v39, v207
	v_mul_f32_e32 v30, 0xbfb8aa3b, v29
	v_exp_f32_e32 v30, v30
	s_nop 0
	v_add_f32_e32 v30, 1.0, v30
	v_rcp_f32_e32 v30, v30
	s_nop 0
	v_mul_f32_e32 v29, v29, v30
	v_mul_f32_e32 v30, v38, v205
	v_fmac_f32_e32 v30, v37, v204
	v_fmac_f32_e32 v30, v39, v206
	v_fmac_f32_e32 v30, v40, v207
	v_mul_f32_e32 v31, 0xbfb8aa3b, v30
	v_exp_f32_e32 v31, v31
	s_nop 0
	v_add_f32_e32 v31, 1.0, v31
	v_rcp_f32_e32 v31, v31
	s_nop 0
	v_mul_f32_e32 v30, v30, v31
	v_add_u32_e32 v31, 0x4600, v2
	ds_write2_b32 v31, v29, v30 offset0:70 offset1:135
	v_mul_f32_e32 v29, v39, v205
	v_fmac_f32_e32 v29, v38, v204
	v_fmac_f32_e32 v29, v40, v206
	v_fmac_f32_e32 v29, v41, v207
	v_mul_f32_e32 v30, 0xbfb8aa3b, v29
	v_exp_f32_e32 v30, v30
	s_nop 0
	v_add_f32_e32 v30, 1.0, v30
	v_rcp_f32_e32 v30, v30
	s_nop 0
	v_mul_f32_e32 v29, v29, v30
	v_mul_f32_e32 v30, v40, v205
	v_fmac_f32_e32 v30, v39, v204
	v_fmac_f32_e32 v30, v41, v206
	v_fmac_f32_e32 v30, v42, v207
	v_mul_f32_e32 v31, 0xbfb8aa3b, v30
	v_exp_f32_e32 v31, v31
	s_nop 0
	v_add_f32_e32 v31, 1.0, v31
	v_rcp_f32_e32 v31, v31
	s_nop 0
	v_mul_f32_e32 v30, v30, v31
	v_add_u32_e32 v31, 0x4800, v2
	ds_write2_b32 v31, v29, v30 offset0:72 offset1:137
	v_mul_f32_e32 v29, v41, v205
	v_fmac_f32_e32 v29, v40, v204
	v_fmac_f32_e32 v29, v42, v206
	v_fmac_f32_e32 v29, v43, v207
	v_mul_f32_e32 v30, 0xbfb8aa3b, v29
	v_exp_f32_e32 v30, v30
	s_nop 0
	v_add_f32_e32 v30, 1.0, v30
	v_rcp_f32_e32 v30, v30
	s_nop 0
	v_mul_f32_e32 v29, v29, v30
	v_mul_f32_e32 v30, v42, v205
	v_fmac_f32_e32 v30, v41, v204
	v_fmac_f32_e32 v30, v43, v206
	v_fmac_f32_e32 v30, v44, v207
	v_mul_f32_e32 v31, 0xbfb8aa3b, v30
	v_exp_f32_e32 v31, v31
	s_nop 0
	v_add_f32_e32 v31, 1.0, v31
	v_rcp_f32_e32 v31, v31
	s_nop 0
	v_mul_f32_e32 v30, v30, v31
	v_add_u32_e32 v31, 0x4a00, v2
	ds_write2_b32 v31, v29, v30 offset0:74 offset1:139
	v_mul_f32_e32 v29, v43, v205
	v_fmac_f32_e32 v29, v42, v204
	v_fmac_f32_e32 v29, v44, v206
	v_fmac_f32_e32 v29, v45, v207
	v_mul_f32_e32 v30, 0xbfb8aa3b, v29
	v_exp_f32_e32 v30, v30
	s_nop 0
	v_add_f32_e32 v30, 1.0, v30
	v_rcp_f32_e32 v30, v30
	s_nop 0
	v_mul_f32_e32 v29, v29, v30
	v_mul_f32_e32 v30, v44, v205
	v_fmac_f32_e32 v30, v43, v204
	v_fmac_f32_e32 v30, v45, v206
	v_fmac_f32_e32 v30, v46, v207
	v_mul_f32_e32 v31, 0xbfb8aa3b, v30
	v_exp_f32_e32 v31, v31
	s_nop 0
	v_add_f32_e32 v31, 1.0, v31
	v_rcp_f32_e32 v31, v31
	s_nop 0
	v_mul_f32_e32 v30, v30, v31
	v_add_u32_e32 v31, 0x4c00, v2
	ds_write2_b32 v31, v29, v30 offset0:76 offset1:141
	v_mul_f32_e32 v29, v45, v205
	v_mul_f32_e32 v3, v46, v205
	v_fmac_f32_e32 v29, v44, v204
	v_fmac_f32_e32 v3, v45, v204
	v_fmac_f32_e32 v29, v46, v206
	v_fmac_f32_e32 v3, v47, v206
	v_fmac_f32_e32 v29, v47, v207
	v_fmac_f32_e32 v3, v48, v207
	v_mul_f32_e32 v30, 0xbfb8aa3b, v29
	v_mul_f32_e32 v1, 0xbfb8aa3b, v3
	v_exp_f32_e32 v30, v30
	v_exp_f32_e32 v1, v1
	v_add_f32_e32 v30, 1.0, v30
	v_add_f32_e32 v1, 1.0, v1
	v_rcp_f32_e32 v30, v30
	v_rcp_f32_e32 v1, v1
	v_mul_f32_e32 v29, v29, v30
	v_mul_f32_e32 v1, v3, v1
	ds_write_b32 v2, v29 offset:20280
	ds_write_b32 v4, v1 offset:16640
	v_lshl_add_u64 v[30:31], v[6:7], 0, vcc
	s_waitcnt vmcnt(0)
	s_nop 0
	v_lshlrev_b32_e32 v8, 16, v11
	v_lshlrev_b32_e32 v7, 16, v10
	v_cndmask_b32_e64 v8, 0, v8, s[44:45]
	v_cndmask_b32_e64 v7, 0, v7, s[42:43]
	v_lshlrev_b32_e32 v9, 16, v12
	v_lshlrev_b32_e32 v11, 16, v14
	v_lshlrev_b32_e32 v14, 16, v17
	v_lshlrev_b32_e32 v17, 16, v20
	v_lshlrev_b32_e32 v20, 16, v23
	v_lshlrev_b32_e32 v23, 16, v26
	v_cndmask_b32_e64 v9, 0, v9, s[46:47]
	v_lshlrev_b32_e32 v10, 16, v13
	v_cndmask_b32_e64 v10, 0, v10, s[48:49]
	v_cndmask_b32_e64 v11, 0, v11, s[50:51]
	v_lshlrev_b32_e32 v12, 16, v15
	v_cndmask_b32_e64 v12, 0, v12, s[52:53]
	v_lshlrev_b32_e32 v13, 16, v16
	v_cndmask_b32_e64 v13, 0, v13, s[54:55]
	v_cndmask_b32_e64 v14, 0, v14, s[56:57]
	v_lshlrev_b32_e32 v15, 16, v18
	v_cndmask_b32_e64 v15, 0, v15, s[58:59]
	v_lshlrev_b32_e32 v16, 16, v19
	v_cndmask_b32_e64 v16, 0, v16, s[60:61]
	v_cndmask_b32_e64 v17, 0, v17, s[62:63]
	v_lshlrev_b32_e32 v18, 16, v21
	v_cndmask_b32_e64 v18, 0, v18, s[64:65]
	v_lshlrev_b32_e32 v19, 16, v22
	v_cndmask_b32_e64 v19, 0, v19, s[66:67]
	v_cndmask_b32_e64 v20, 0, v20, s[68:69]
	v_lshlrev_b32_e32 v21, 16, v24
	v_cndmask_b32_e64 v21, 0, v21, s[70:71]
	v_lshlrev_b32_e32 v22, 16, v25
	v_cndmask_b32_e64 v22, 0, v22, s[72:73]
	v_cndmask_b32_e64 v23, 0, v23, s[74:75]
	v_lshlrev_b32_e32 v24, 16, v27
	v_cndmask_b32_e64 v24, 0, v24, s[76:77]
	v_lshlrev_b32_e32 v25, 16, v28
	v_cndmask_b32_e64 v25, 0, v25, s[78:79]
	v_cmp_lt_i32_e64 s[42:43], 63, v68
	v_cmp_gt_i32_e64 s[44:45], 64, v68
	v_mul_f32_e32 v26, v8, v209
	v_fmac_f32_e32 v26, v7, v208
	v_fmac_f32_e32 v26, v9, v210
	v_fmac_f32_e32 v26, v10, v211
	v_mul_f32_e32 v7, 0xbfb8aa3b, v26
	v_exp_f32_e32 v7, v7
	s_nop 0
	v_add_f32_e32 v7, 1.0, v7
	v_rcp_f32_e32 v7, v7
	s_nop 0
	v_mul_f32_e32 v7, v26, v7
	v_mul_f32_e32 v26, v9, v209
	v_fmac_f32_e32 v26, v8, v208
	v_fmac_f32_e32 v26, v10, v210
	v_fmac_f32_e32 v26, v11, v211
	v_mul_f32_e32 v8, 0xbfb8aa3b, v26
	v_exp_f32_e32 v8, v8
	s_nop 0
	v_add_f32_e32 v8, 1.0, v8
	v_rcp_f32_e32 v8, v8
	s_nop 0
	v_mul_f32_e32 v8, v26, v8
	v_add_u32_e32 v26, 0x8000, v2
	ds_write2_b32 v26, v7, v8 offset0:128 offset1:193
	v_mul_f32_e32 v7, v10, v209
	v_fmac_f32_e32 v7, v9, v208
	v_fmac_f32_e32 v7, v11, v210
	v_fmac_f32_e32 v7, v12, v211
	v_mul_f32_e32 v8, 0xbfb8aa3b, v7
	v_exp_f32_e32 v8, v8
	s_nop 0
	v_add_f32_e32 v8, 1.0, v8
	v_rcp_f32_e32 v8, v8
	s_nop 0
	v_mul_f32_e32 v7, v7, v8
	v_mul_f32_e32 v8, v11, v209
	v_fmac_f32_e32 v8, v10, v208
	v_fmac_f32_e32 v8, v12, v210
	v_fmac_f32_e32 v8, v13, v211
	v_mul_f32_e32 v9, 0xbfb8aa3b, v8
	v_exp_f32_e32 v9, v9
	s_nop 0
	v_add_f32_e32 v9, 1.0, v9
	v_rcp_f32_e32 v9, v9
	s_nop 0
	v_mul_f32_e32 v8, v8, v9
	v_add_u32_e32 v9, 0x8400, v2
	ds_write2_b32 v9, v7, v8 offset0:2 offset1:67
	v_mul_f32_e32 v7, v12, v209
	v_fmac_f32_e32 v7, v11, v208
	v_fmac_f32_e32 v7, v13, v210
	v_fmac_f32_e32 v7, v14, v211
	v_mul_f32_e32 v8, 0xbfb8aa3b, v7
	v_exp_f32_e32 v8, v8
	s_nop 0
	v_add_f32_e32 v8, 1.0, v8
	v_rcp_f32_e32 v8, v8
	s_nop 0
	v_mul_f32_e32 v7, v7, v8
	v_mul_f32_e32 v8, v13, v209
	v_fmac_f32_e32 v8, v12, v208
	v_fmac_f32_e32 v8, v14, v210
	v_fmac_f32_e32 v8, v15, v211
	v_mul_f32_e32 v10, 0xbfb8aa3b, v8
	v_exp_f32_e32 v10, v10
	s_nop 0
	v_add_f32_e32 v10, 1.0, v10
	v_rcp_f32_e32 v10, v10
	s_nop 0
	v_mul_f32_e32 v8, v8, v10
	ds_write2_b32 v9, v7, v8 offset0:132 offset1:197
	v_mul_f32_e32 v7, v14, v209
	v_fmac_f32_e32 v7, v13, v208
	v_fmac_f32_e32 v7, v15, v210
	v_fmac_f32_e32 v7, v16, v211
	v_mul_f32_e32 v8, 0xbfb8aa3b, v7
	v_exp_f32_e32 v8, v8
	s_nop 0
	v_add_f32_e32 v8, 1.0, v8
	v_rcp_f32_e32 v8, v8
	s_nop 0
	v_mul_f32_e32 v7, v7, v8
	v_mul_f32_e32 v8, v15, v209
	v_fmac_f32_e32 v8, v14, v208
	v_fmac_f32_e32 v8, v16, v210
	v_fmac_f32_e32 v8, v17, v211
	v_mul_f32_e32 v9, 0xbfb8aa3b, v8
	v_exp_f32_e32 v9, v9
	s_nop 0
	v_add_f32_e32 v9, 1.0, v9
	v_rcp_f32_e32 v9, v9
	s_nop 0
	v_mul_f32_e32 v8, v8, v9
	v_add_u32_e32 v9, 0x8800, v2
	ds_write2_b32 v9, v7, v8 offset0:6 offset1:71
	v_mul_f32_e32 v7, v16, v209
	v_fmac_f32_e32 v7, v15, v208
	v_fmac_f32_e32 v7, v17, v210
	v_fmac_f32_e32 v7, v18, v211
	v_mul_f32_e32 v8, 0xbfb8aa3b, v7
	v_exp_f32_e32 v8, v8
	s_nop 0
	v_add_f32_e32 v8, 1.0, v8
	v_rcp_f32_e32 v8, v8
	s_nop 0
	v_mul_f32_e32 v7, v7, v8
	v_mul_f32_e32 v8, v17, v209
	v_fmac_f32_e32 v8, v16, v208
	v_fmac_f32_e32 v8, v18, v210
	v_fmac_f32_e32 v8, v19, v211
	v_mul_f32_e32 v10, 0xbfb8aa3b, v8
	v_exp_f32_e32 v10, v10
	s_nop 0
	v_add_f32_e32 v10, 1.0, v10
	v_rcp_f32_e32 v10, v10
	s_nop 0
	v_mul_f32_e32 v8, v8, v10
	ds_write2_b32 v9, v7, v8 offset0:136 offset1:201
	v_mul_f32_e32 v7, v18, v209
	v_fmac_f32_e32 v7, v17, v208
	v_fmac_f32_e32 v7, v19, v210
	v_fmac_f32_e32 v7, v20, v211
	v_mul_f32_e32 v8, 0xbfb8aa3b, v7
	v_exp_f32_e32 v8, v8
	s_nop 0
	v_add_f32_e32 v8, 1.0, v8
	v_rcp_f32_e32 v8, v8
	s_nop 0
	v_mul_f32_e32 v7, v7, v8
	v_mul_f32_e32 v8, v19, v209
	v_fmac_f32_e32 v8, v18, v208
	v_fmac_f32_e32 v8, v20, v210
	v_fmac_f32_e32 v8, v21, v211
	v_mul_f32_e32 v9, 0xbfb8aa3b, v8
	v_exp_f32_e32 v9, v9
	s_nop 0
	v_add_f32_e32 v9, 1.0, v9
	v_rcp_f32_e32 v9, v9
	s_nop 0
	v_mul_f32_e32 v8, v8, v9
	v_add_u32_e32 v9, 0x8c00, v2
	ds_write2_b32 v9, v7, v8 offset0:10 offset1:75
	v_mul_f32_e32 v7, v20, v209
	v_fmac_f32_e32 v7, v19, v208
	v_fmac_f32_e32 v7, v21, v210
	v_fmac_f32_e32 v7, v22, v211
	v_mul_f32_e32 v8, 0xbfb8aa3b, v7
	v_exp_f32_e32 v8, v8
	s_nop 0
	v_add_f32_e32 v8, 1.0, v8
	v_rcp_f32_e32 v8, v8
	s_nop 0
	v_mul_f32_e32 v7, v7, v8
	v_mul_f32_e32 v8, v21, v209
	v_fmac_f32_e32 v8, v20, v208
	v_fmac_f32_e32 v8, v22, v210
	v_fmac_f32_e32 v8, v23, v211
	v_mul_f32_e32 v10, 0xbfb8aa3b, v8
	v_exp_f32_e32 v10, v10
	s_nop 0
	v_add_f32_e32 v10, 1.0, v10
	v_rcp_f32_e32 v10, v10
	s_nop 0
	v_mul_f32_e32 v8, v8, v10
	ds_write2_b32 v9, v7, v8 offset0:140 offset1:205
	v_mul_f32_e32 v7, v22, v209
	v_fmac_f32_e32 v7, v21, v208
	v_fmac_f32_e32 v7, v23, v210
	v_fmac_f32_e32 v7, v24, v211
	v_mul_f32_e32 v8, 0xbfb8aa3b, v7
	v_exp_f32_e32 v8, v8
	s_nop 0
	v_add_f32_e32 v8, 1.0, v8
	v_rcp_f32_e32 v8, v8
	s_nop 0
	v_mul_f32_e32 v7, v7, v8
	ds_write_b32 v2, v7 offset:36920
	v_mul_f32_e32 v2, v23, v209
	v_fmac_f32_e32 v2, v22, v208
	v_fmac_f32_e32 v2, v24, v210
	v_fmac_f32_e32 v2, v25, v211
	v_mul_f32_e32 v1, 0xbfb8aa3b, v2
	v_exp_f32_e32 v1, v1
	s_nop 0
	v_add_f32_e32 v1, 1.0, v1
	v_rcp_f32_e32 v1, v1
	s_nop 0
	v_mul_f32_e32 v1, v2, v1
	ds_write_b32 v4, v1 offset:33280
	v_lshlrev_b32_e32 v1, 2, v68
	v_mov_b32_e32 v3, v210
	v_mov_b32_e32 v5, v209
	v_mov_b32_e32 v6, v211
	v_mov_b32_e32 v49, v207
	s_and_saveexec_b64 s[46:47], s[44:45]
	s_cbranch_execz .LBB0_368
	v_ashrrev_i32_e32 v69, 31, v68
	v_lshl_add_u64 v[2:3], s[40:41], 0, v[68:69]
	v_lshlrev_b64 v[2:3], 7, v[2:3]
	v_lshl_add_u64 v[2:3], s[80:81], 0, v[2:3]
	s_lshl_b32 s84, s26, 2
	v_lshl_add_u64 v[2:3], v[2:3], 0, s[84:85]
	s_or_b32 s84, s26, s94
	s_mov_b64 s[2:3], 0x10000000
	s_lshl_b64 s[40:41], s[84:85], 2
	v_lshl_add_u64 v[4:5], v[2:3], 0, s[2:3]
	s_waitcnt lgkmcnt(0)
	s_add_u32 s2, s50, s40
	v_add_co_u32_e32 v2, vcc, 0x10000000, v2
	s_addc_u32 s3, s51, s41
	s_nop 0
	v_addc_co_u32_e32 v3, vcc, 0, v3, vcc
	v_add_u32_e32 v10, -1, v229
	v_and_b32_e32 v3, 64, v229
	s_add_u32 s2, s48, s40
	s_addc_u32 s3, s49, s41
	s_waitcnt vmcnt(0)
	s_mov_b32 s2, 0xbfb8aa3b
	s_mov_b32 s3, 0x3f2aaaab
	v_cmp_lt_i32_e32 vcc, v10, v3
	s_mov_b32 s26, 0x3f317218
	v_mov_b32_e32 v7, 0x3ecc95a3
	v_cndmask_b32_e32 v10, v10, v229, vcc
	s_mov_b32 s27, 0x7f800000
	v_mov_b32_e32 v8, 0x7fc00000
	v_mov_b32_e32 v9, 0xff800000
	s_mov_b32 s28, 0x33800000
	v_lshlrev_b32_e32 v10, 2, v10
	v_mul_f32_e32 v2, 0xbfb8aa3b, v201
	v_exp_f32_e32 v2, v2
	v_add_f32_e32 v4, v200, v202
	v_mul_f32_e64 v5, |v4|, s2
	v_exp_f32_e32 v11, v5
	v_max_f32_e32 v12, 0, v4
	v_mul_f32_e32 v4, 0x3fb8aa3b, v203
	v_exp_f32_e32 v6, v4
	v_add_f32_e32 v13, 1.0, v11
	v_add_f32_e32 v14, -1.0, v13
	v_frexp_mant_f32_e32 v15, v13
	v_cvt_f64_f32_e32 v[4:5], v13
	v_sub_f32_e32 v16, v14, v13
	v_frexp_exp_i32_f64_e32 v4, v[4:5]
	v_cmp_gt_f32_e32 vcc, s3, v15
	v_sub_f32_e32 v14, v11, v14
	v_add_f32_e32 v5, 1.0, v16
	v_subbrev_co_u32_e32 v4, vcc, 0, v4, vcc
	v_add_f32_e32 v5, v14, v5
	v_sub_u32_e32 v14, 0, v4
	v_cvt_f32_i32_e32 v4, v4
	v_ldexp_f32 v13, v13, v14
	v_ldexp_f32 v5, v5, v14
	v_add_f32_e32 v14, -1.0, v13
	v_add_f32_e32 v15, 1.0, v13
	v_add_f32_e32 v16, 1.0, v14
	v_add_f32_e32 v17, -1.0, v15
	v_sub_f32_e32 v16, v13, v16
	v_sub_f32_e32 v13, v13, v17
	v_mul_f32_e32 v17, 0x3f317218, v4
	v_add_f32_e32 v16, v5, v16
	v_add_f32_e32 v5, v5, v13
	v_fma_f32 v13, v4, s26, -v17
	v_add_f32_e32 v18, v14, v16
	v_add_f32_e32 v19, v15, v5
	v_fmac_f32_e32 v13, 0xb102e308, v4
	v_sub_f32_e32 v4, v18, v14
	v_sub_f32_e32 v14, v19, v15
	v_rcp_f32_e32 v15, v19
	v_add_f32_e32 v20, v17, v13
	v_sub_f32_e32 v5, v5, v14
	v_sub_f32_e32 v14, v20, v17
	v_sub_f32_e32 v13, v13, v14
	v_mul_f32_e32 v14, v18, v15
	v_sub_f32_e32 v4, v16, v4
	v_mul_f32_e32 v16, v19, v14
	v_fma_f32 v17, v14, v19, -v16
	v_fmac_f32_e32 v17, v14, v5
	v_add_f32_e32 v21, v16, v17
	v_sub_f32_e32 v22, v18, v21
	v_sub_f32_e32 v16, v21, v16
	v_sub_f32_e32 v18, v18, v22
	v_sub_f32_e32 v16, v16, v17
	v_sub_f32_e32 v17, v18, v21
	v_add_f32_e32 v4, v4, v17
	v_add_f32_e32 v4, v16, v4
	v_add_f32_e32 v16, v22, v4
	v_mul_f32_e32 v17, v15, v16
	v_sub_f32_e32 v18, v22, v16
	v_mul_f32_e32 v21, v19, v17
	v_add_f32_e32 v4, v4, v18
	v_add_f32_e32 v18, v14, v17
	v_fma_f32 v19, v17, v19, -v21
	v_sub_f32_e32 v14, v18, v14
	v_fmac_f32_e32 v19, v17, v5
	v_sub_f32_e32 v5, v17, v14
	v_add_f32_e32 v14, v21, v19
	v_sub_f32_e32 v17, v14, v21
	v_sub_f32_e32 v21, v16, v14
	v_sub_f32_e32 v16, v16, v21
	v_sub_f32_e32 v14, v16, v14
	v_sub_f32_e32 v17, v17, v19
	v_add_f32_e32 v4, v4, v14
	v_add_f32_e32 v4, v17, v4
	v_add_f32_e32 v4, v21, v4
	v_mul_f32_e32 v4, v15, v4
	v_add_f32_e32 v4, v5, v4
	v_add_f32_e32 v5, v18, v4
	v_mul_f32_e32 v14, v5, v5
	v_fmamk_f32 v7, v14, 0x3e9b6dac, v7
	v_sub_f32_e32 v15, v5, v18
	v_ldexp_f32 v16, v5, 1
	v_mul_f32_e32 v5, v5, v14
	v_fmaak_f32 v7, v14, v7, 0x3f2aaada
	v_mul_f32_e32 v5, v5, v7
	v_add_f32_e32 v7, v16, v5
	v_sub_f32_e32 v4, v4, v15
	v_sub_f32_e32 v14, v7, v16
	v_ldexp_f32 v4, v4, 1
	v_sub_f32_e32 v5, v5, v14
	v_add_f32_e32 v4, v4, v5
	v_add_f32_e32 v5, v7, v4
	v_sub_f32_e32 v7, v5, v7
	v_add_f32_e32 v14, v20, v5
	v_sub_f32_e32 v4, v4, v7
	v_sub_f32_e32 v7, v14, v20
	v_sub_f32_e32 v15, v14, v7
	v_sub_f32_e32 v5, v5, v7
	v_add_f32_e32 v7, v13, v4
	v_sub_f32_e32 v15, v20, v15
	v_sub_f32_e32 v16, v7, v13
	v_add_f32_e32 v5, v5, v15
	v_sub_f32_e32 v15, v7, v16
	v_add_f32_e32 v5, v7, v5
	v_sub_f32_e32 v4, v4, v16
	v_sub_f32_e32 v13, v13, v15
	v_add_f32_e32 v7, v14, v5
	v_add_f32_e32 v4, v4, v13
	v_sub_f32_e32 v13, v7, v14
	v_sub_f32_e32 v5, v5, v13
	v_add_f32_e32 v4, v4, v5
	v_add_f32_e32 v4, v7, v4
	v_cmp_neq_f32_e32 vcc, s27, v11
	v_add_f32_e32 v2, 1.0, v2
	s_nop 0
	v_cndmask_b32_e32 v4, v228, v4, vcc
	v_cmp_ngt_f32_e32 vcc, -1.0, v11
	s_nop 1
	v_cndmask_b32_e32 v4, v8, v4, vcc
	v_cmp_neq_f32_e32 vcc, -1.0, v11
	v_add_u32_e32 v8, -2, v229
	s_nop 0
	v_cndmask_b32_e32 v4, v9, v4, vcc
	v_cmp_lt_f32_e64 vcc, |v11|, s28
	s_nop 1
	v_cndmask_b32_e32 v4, v4, v11, vcc
	v_add_f32_e32 v4, v12, v4
	v_mul_f32_e64 v5, v4, -v6
	ds_bpermute_b32 v7, v10, v5
	v_cmp_lt_i32_e32 vcc, v8, v3
	s_waitcnt lgkmcnt(0)
	v_fma_f32 v4, v4, -v6, v7
	v_cndmask_b32_e32 v8, v8, v229, vcc
	v_cmp_eq_u32_e32 vcc, 0, v34
	v_lshlrev_b32_e32 v8, 2, v8
	v_add_u32_e32 v6, -4, v229
	v_cndmask_b32_e32 v4, v4, v5, vcc
	ds_bpermute_b32 v5, v8, v4
	v_cmp_lt_i32_e32 vcc, v6, v3
	s_waitcnt lgkmcnt(0)
	v_add_f32_e32 v5, v4, v5
	v_cndmask_b32_e32 v6, v6, v229, vcc
	v_cmp_gt_u32_e32 vcc, 2, v34
	s_nop 1
	v_cndmask_b32_e32 v4, v5, v4, vcc
	v_lshlrev_b32_e32 v5, 2, v6
	ds_bpermute_b32 v5, v5, v4
	v_add_u32_e32 v6, -8, v229
	v_cmp_gt_u32_e32 vcc, 4, v34
	s_waitcnt lgkmcnt(0)
	v_add_f32_e32 v5, v4, v5
	v_cndmask_b32_e32 v4, v5, v4, vcc
	v_cmp_lt_i32_e32 vcc, v6, v3
	s_nop 1
	v_cndmask_b32_e32 v5, v6, v229, vcc
	v_lshlrev_b32_e32 v5, 2, v5
	ds_bpermute_b32 v5, v5, v4
	v_add_u32_e32 v6, -16, v229
	v_cmp_gt_u32_e32 vcc, 8, v34
	s_waitcnt lgkmcnt(0)
	v_add_f32_e32 v5, v4, v5
	v_cndmask_b32_e32 v4, v5, v4, vcc
	v_cmp_lt_i32_e32 vcc, v6, v3
	s_nop 1
	v_cndmask_b32_e32 v5, v6, v229, vcc
	v_lshlrev_b32_e32 v5, 2, v5
	ds_bpermute_b32 v5, v5, v4
	v_cmp_gt_u32_e32 vcc, 16, v34
	s_waitcnt lgkmcnt(0)
	v_add_f32_e32 v5, v4, v5
	v_cndmask_b32_e32 v4, v5, v4, vcc
	v_subrev_u32_e32 v5, 32, v229
	v_cmp_lt_i32_e32 vcc, v5, v3
	s_nop 1
	v_cndmask_b32_e32 v3, v5, v229, vcc
	v_lshlrev_b32_e32 v3, 2, v3
	ds_bpermute_b32 v3, v3, v4
	v_cmp_gt_u32_e32 vcc, 32, v34
	v_add_u32_e32 v5, 0x10300, v1
	s_waitcnt lgkmcnt(0)
	v_add_f32_e32 v3, v4, v3
	v_cndmask_b32_e32 v3, v3, v4, vcc
	v_rcp_f32_e32 v4, v2
	v_mul_f32_e32 v2, 0x3fb8aa3b, v3
	v_exp_f32_e32 v2, v2
	ds_write_b32 v5, v3
	v_add_u32_e32 v3, 0x10400, v1
	ds_write_b32 v3, v4
	v_add_u32_e32 v3, 0x10500, v1
	ds_write_b32 v3, v2
	v_mul_f32_e32 v3, v4, v2
	v_add_u32_e32 v4, 0x10600, v1
	v_cmp_eq_u32_e32 vcc, 63, v68
	ds_write_b32 v4, v3
	s_and_b64 exec, exec, vcc
	s_cbranch_execz .LBB0_368
	s_lshl_b64 s[2:3], s[86:87], 2
	s_add_u32 s2, s80, s2
	s_addc_u32 s3, s81, s3
	global_store_dword v225, v2, s[2:3]
